# s15 + even-tile global loads (next K/V tile) issued inside the QK MFMA gaps instead of at the head of the P.V segment
# baseline (speedup 1.0000x reference)
; __device__ __forceinline__ void partialSM(f32x16& p0, f32x16& p1, float& m_reg, float& mn, float& alpha) {
;     ...
;   float mnC = -mn * C;
;   for (int r = 0; r < 16; ++r) p0[r] = fmaf(p0[r], C, mnC); for (int r = 0; r < 16; ++r) p1[r] = fmaf(p1[r], C, mnC);
;   for (int r = 0; r < 16; ++r) p0[r] = __builtin_amdgcn_exp2f(p0[r]);
; }
; __device__ __forceinline__ void finishSM(f32x16& p0, f32x16& p1, float alpha, float& l_reg, bf16x8& pa0, bf16x8& pa1, bf16x8& pa2, bf16x8& pa3) {
;   for (int r = 0; r < 16; ++r) p1[r] = __builtin_amdgcn_exp2f(p1[r]);
;   float ps = 0; for (int r = 0; r < 16; ++r) ps += p0[r]; for (int r = 0; r < 16; ++r) ps += p1[r];
;   { auto rr = __builtin_amdgcn_permlane32_swap(__float_as_uint(ps), __float_as_uint(ps), false, false);
;     ps = __uint_as_float(rr[0]) + __uint_as_float(rr[1]); }
;   l_reg = l_reg * alpha + ps;
;     ...
;   PK4(p0, 0, pa0); PK4(p0, 8, pa1); PK4(p1, 0, pa2); PK4(p1, 8, pa3);
;     ...
; }
; __device__ __forceinline__ void qkt(f32x16& p0, f32x16& p1, const bf16* Ks, const bf16x8* qr, int r32, int hi) {
;   p0 = f32x16{}; p1 = f32x16{};
;   for (int d0 = 0; d0 < 8; ++d0) { int cb = (d0 * 16 + hi * 8) * 2;
;     bf16x8 b0 = *reinterpret_cast<const bf16x8*>((const char*)Ks + KSWZ(r32, cb));
;     bf16x8 b1 = *reinterpret_cast<const bf16x8*>((const char*)Ks + KSWZ(32 + r32, cb));
;     p0 = __builtin_amdgcn_mfma_f32_32x32x16_bf16(b0, qr[d0], p0, 0, 0, 0);
;     p1 = __builtin_amdgcn_mfma_f32_32x32x16_bf16(b1, qr[d0], p1, 0, 0, 0); }
; }
.LBB0_606:
	v_mov_b32_e32 v162, v80
	v_mov_b32_e32 v163, v81
	v_mov_b32_e32 v164, v82
	v_mov_b32_e32 v175, v83
	v_mov_b32_e32 v176, v84
	v_mov_b32_e32 v177, v85
	v_mov_b32_e32 v165, v86
	v_mov_b32_e32 v174, v87
	v_mov_b32_e32 v166, v88
	v_mov_b32_e32 v167, v89
	v_mov_b32_e32 v172, v90
	v_mov_b32_e32 v173, v91
	v_mov_b32_e32 v168, v92
	v_mov_b32_e32 v169, v93
	v_mov_b32_e32 v170, v94
	v_mov_b32_e32 v171, v95
	v_fmamk_f32 v223, v64, 0x3e0293ee, v213
	v_fmamk_f32 v224, v65, 0x3e0293ee, v213
	v_fmamk_f32 v225, v66, 0x3e0293ee, v213
	v_fmamk_f32 v226, v67, 0x3e0293ee, v213
	v_fmamk_f32 v227, v68, 0x3e0293ee, v213
	v_fmamk_f32 v216, v69, 0x3e0293ee, v213
	v_fmamk_f32 v217, v70, 0x3e0293ee, v213
	v_fmamk_f32 v218, v71, 0x3e0293ee, v213
	v_fmamk_f32 v219, v72, 0x3e0293ee, v213
	v_fmamk_f32 v220, v73, 0x3e0293ee, v213
	v_fmamk_f32 v221, v74, 0x3e0293ee, v213
	v_fmamk_f32 v222, v75, 0x3e0293ee, v213
	v_fmamk_f32 v215, v76, 0x3e0293ee, v213
	v_fmamk_f32 v228, v77, 0x3e0293ee, v213
	v_fmamk_f32 v229, v78, 0x3e0293ee, v213
	v_fmac_f32_e32 v213, 0x3e0293ee, v79
	ds_read_b128 v[64:67], v192 offset:32768
	ds_read_b128 v[68:71], v192 offset:40960
	ds_read_b128 v[242:245], v201 offset:32768
	ds_read_b128 v[246:249], v201 offset:40960
	v_add_f32_e32 v230, 0, v162
	v_add_f32_e32 v230, v163, v230
	s_waitcnt lgkmcnt(3)
	v_mfma_f32_32x32x16_bf16 v[80:95], v[64:67], v[126:129], 0
	v_add_f32_e32 v230, v164, v230
	v_add_f32_e32 v230, v175, v230
	v_add_f32_e32 v230, v176, v230
	v_add_f32_e32 v230, v177, v230
	v_add_f32_e32 v230, v165, v230
	v_add_f32_e32 v230, v174, v230
	v_add_f32_e32 v230, v166, v230
	s_waitcnt lgkmcnt(2)
	v_mfma_f32_32x32x16_bf16 v[64:79], v[68:71], v[126:129], 0
	v_add_f32_e32 v230, v167, v230
	v_add_f32_e32 v230, v172, v230
	v_add_f32_e32 v230, v173, v230
	v_exp_f32_e32 v223, v223
	v_add_f32_e32 v230, v168, v230
	v_exp_f32_e32 v224, v224
	v_add_f32_e32 v230, v169, v230
	s_waitcnt lgkmcnt(1)
	v_mfma_f32_32x32x16_bf16 v[80:95], v[242:245], v[122:125], v[80:95]
	v_exp_f32_e32 v225, v225
	v_add_f32_e32 v230, v170, v230
	v_exp_f32_e32 v226, v226
	v_add_f32_e32 v230, v171, v230
	v_exp_f32_e32 v227, v227
	v_add_f32_e32 v230, v223, v230
	v_exp_f32_e32 v216, v216
	s_waitcnt lgkmcnt(0)
	v_mfma_f32_32x32x16_bf16 v[64:79], v[246:249], v[122:125], v[64:79]
	ds_read_b128 v[242:245], v200 offset:32768
	ds_read_b128 v[246:249], v200 offset:40960
	v_add_f32_e32 v230, v224, v230
	v_exp_f32_e32 v217, v217
	v_add_f32_e32 v230, v225, v230
	v_exp_f32_e32 v218, v218
	v_add_f32_e32 v230, v226, v230
	v_exp_f32_e32 v219, v219
	s_waitcnt lgkmcnt(1)
	v_mfma_f32_32x32x16_bf16 v[80:95], v[242:245], v[134:137], v[80:95]
	v_add_f32_e32 v230, v227, v230
	v_exp_f32_e32 v220, v220
	v_add_f32_e32 v230, v216, v230
	v_exp_f32_e32 v221, v221
	v_add_f32_e32 v230, v217, v230
	v_exp_f32_e32 v222, v222
	v_add_f32_e32 v230, v218, v230
	s_waitcnt lgkmcnt(0)
	v_mfma_f32_32x32x16_bf16 v[64:79], v[246:249], v[134:137], v[64:79]
	ds_read_b128 v[242:245], v195 offset:32768
	ds_read_b128 v[246:249], v195 offset:40960
	v_exp_f32_e32 v215, v215
	v_add_f32_e32 v230, v219, v230
	v_exp_f32_e32 v228, v228
	v_add_f32_e32 v230, v220, v230
	v_exp_f32_e32 v229, v229
	v_add_f32_e32 v230, v221, v230
	s_waitcnt lgkmcnt(1)
	v_mfma_f32_32x32x16_bf16 v[80:95], v[242:245], v[130:133], v[80:95]
	v_exp_f32_e32 v213, v213
	v_add_f32_e32 v230, v222, v230
	v_add_f32_e32 v230, v215, v230
	v_add_f32_e32 v230, v228, v230
	v_add_f32_e32 v230, v229, v230
	v_add_f32_e32 v231, v213, v230
	v_mov_b32_e32 v241, v231
	s_waitcnt lgkmcnt(0)
	v_mfma_f32_32x32x16_bf16 v[64:79], v[246:249], v[130:133], v[64:79]
	ds_read_b128 v[242:245], v194 offset:32768
	ds_read_b128 v[246:249], v194 offset:40960
	v_cvt_pk_bf16_f32 v162, v162, v163
	v_cvt_pk_bf16_f32 v163, v164, v175
	v_cvt_pk_bf16_f32 v164, v176, v177
	v_cvt_pk_bf16_f32 v165, v165, v174
	v_cvt_pk_bf16_f32 v166, v166, v167
	v_cvt_pk_bf16_f32 v167, v172, v173
	s_waitcnt lgkmcnt(1)
	v_mfma_f32_32x32x16_bf16 v[80:95], v[242:245], v[118:121], v[80:95]
	v_cvt_pk_bf16_f32 v168, v168, v169
	v_cvt_pk_bf16_f32 v169, v170, v171
	v_cvt_pk_bf16_f32 v170, v223, v224
	v_cvt_pk_bf16_f32 v171, v225, v226
	v_cvt_pk_bf16_f32 v172, v227, v216
	v_cvt_pk_bf16_f32 v173, v217, v218
	v_cvt_pk_bf16_f32 v174, v219, v220
	s_waitcnt lgkmcnt(0)
	v_mfma_f32_32x32x16_bf16 v[64:79], v[246:249], v[118:121], v[64:79]
	ds_read_b128 v[242:245], v193 offset:32768
	ds_read_b128 v[246:249], v193 offset:40960
	v_cvt_pk_bf16_f32 v175, v221, v222
	v_cvt_pk_bf16_f32 v176, v215, v228
	v_cvt_pk_bf16_f32 v177, v229, v213
	v_permlane32_swap_b32_e32 v231, v241
	v_permlane32_swap_b32_e32 v162, v164
	s_waitcnt lgkmcnt(1)
	v_mfma_f32_32x32x16_bf16 v[80:95], v[242:245], v[114:117], v[80:95]
	v_permlane32_swap_b32_e32 v163, v165
	v_permlane32_swap_b32_e32 v166, v168
	v_permlane32_swap_b32_e32 v167, v169
	v_permlane32_swap_b32_e32 v170, v172
	s_waitcnt lgkmcnt(0)
	v_mfma_f32_32x32x16_bf16 v[64:79], v[246:249], v[114:117], v[64:79]
	ds_read_b128 v[242:245], v207 offset:32768
	ds_read_b128 v[246:249], v207 offset:40960
	v_permlane32_swap_b32_e32 v171, v173
	v_permlane32_swap_b32_e32 v174, v176
	v_permlane32_swap_b32_e32 v175, v177
	s_cmp_ge_u32 s40, s41
	s_cselect_b64 s[12:13], -1, 0
	s_and_b64 vcc, exec, s[12:13]
	s_cbranch_vccnz .Lattn_ldskip
	v_add_co_u32_e32 v98, vcc, 0xffff8000, v182
	s_nop 1
	v_addc_co_u32_e32 v99, vcc, -1, v183, vcc
	v_add_co_u32_e32 v102, vcc, 0xff6f8000, v182
	s_nop 1
	v_addc_co_u32_e32 v103, vcc, -1, v183, vcc
	v_add_co_u32_e32 v142, vcc, 0xff700000, v182
	global_load_dwordx4 v[98:101], v[98:99], off
	s_nop 0
	global_load_dwordx4 v[102:105], v[102:103], off
	v_addc_co_u32_e32 v143, vcc, -1, v183, vcc
	global_load_dwordx4 v[138:141], v[182:183], off
	s_nop 0
	global_load_dwordx4 v[142:145], v[142:143], off
.Lattn_ldskip:
	s_waitcnt lgkmcnt(1)
	v_mfma_f32_32x32x16_bf16 v[80:95], v[242:245], v[110:113], v[80:95]
	s_waitcnt lgkmcnt(0)
	v_mfma_f32_32x32x16_bf16 v[64:79], v[246:249], v[110:113], v[64:79]
	ds_read_b128 v[242:245], v206 offset:32768
	ds_read_b128 v[246:249], v206 offset:40960
	s_waitcnt lgkmcnt(1)
	v_mfma_f32_32x32x16_bf16 v[80:95], v[242:245], v[106:109], v[80:95]
	s_waitcnt lgkmcnt(0)
	v_mfma_f32_32x32x16_bf16 v[64:79], v[246:249], v[106:109], v[64:79]
